# swa: query-row and sink loads issued before the K/V staging loads (one exposed global round trip per item)
# baseline (speedup 1.0000x reference)
; __device__ __forceinline__ unsigned pk2(float lo, float hi) { f32x2c v = {lo, hi}; return __builtin_bit_cast(unsigned, __builtin_convertvector(v, bf16x2c)); }
; __device__ __forceinline__ void swa_phase(const Params& p, LAS unsigned char* lds8, const int e) {
;     ...
;         for (int idx = tid; idx < KROWS * 16; idx += 512) {
;             const int r = idx >> 4, c = (idx & 15) * 4;
;             f32x4 kv = (f32x4){0.f, 0.f, 0.f, 0.f}, vv = kv;
;             if (!samp) { const int pos = q0 - 127 + r; if (pos >= 0 && r < 159) { const float* src = PROJ + (size_t)(b * SEQ + pos) * IN_EVEN + 5120 + kh * 64 + c; kv = *(const f32x4*)src; vv = *(const f32x4*)(src + 256); } }
;             else if (r < 128) { const size_t o_ = ((size_t)b * 128 + r) * 256 + kh * 64 + c; kv = *(const f32x4*)(cK + o_); vv = *(const f32x4*)(cV + o_); }
;             else if (r < 136) { const float* src = PROJ + (size_t)(MP + b * DSEQ + r - 128) * IN_EVEN + 5120 + kh * 64 + c; kv = *(const f32x4*)src; vv = *(const f32x4*)(src + 256); }
;     ...
;             const int qi = 16 * sub + fr;
;             const bool qreal = !samp || qi < 8;
;             const int rq = samp ? 128 + qi : 127 + qi;
;             const int mtok = samp ? MP + b * DSEQ + (qi & 7) : b * SEQ + q0 + qi;
;             const int head = kh * 4 + hh;
;             const float sink = IN(16)[e * 16 + head];
;             bf16x8 qf[2];
;             { const float* qp = PROJ + (size_t)mtok * IN_EVEN + 4096 + head * 64 + 8 * fq;
; #pragma unroll
;               for (int ks = 0; ks < 2; ++ks) { const f32x4 a = *(const f32x4*)(qp + 32 * ks) * 0.125f, c2 = *(const f32x4*)(qp + 32 * ks + 4) * 0.125f;
;                   u32x4 w; w.x = pk2(a[0], a[1]); w.y = pk2(a[2], a[3]); w.z = pk2(c2[0], c2[1]); w.w = pk2(c2[2], c2[3]); qf[ks] = __builtin_bit_cast(bf16x8, w); } }
.LBB0_1133:
	s_and_b32 s54, s12, 3
	s_barrier
	s_movk_i32 s12, 0x78
	s_ashr_i32 s13, s12, 31
	s_add_u32 s12, s0, s12
	s_addc_u32 s13, s1, s13
	s_load_dwordx2 s[12:13], s[12:13], 0x0
	s_lshl_b32 s15, s54, 2
	v_or_b32_e32 v202, s15, v34
	v_ashrrev_i32_e32 v203, 31, v202
	s_waitcnt lgkmcnt(0)
	v_lshl_add_u64 v[202:203], v[202:203], 2, s[12:13]
	global_load_dword v201, v[202:203], off
	s_andn2_b64 vcc, exec, s[24:25]
	s_cbranch_vccnz .Lsw_q_prompt
	v_lshl_add_u32 v24, s14, 3, v32
	s_branch .Lsw_q_go
.Lsw_q_prompt:
	s_lshl_b32 s72, s14, 12
	s_or_b32 s72, s72, s39
	v_or_b32_e32 v24, s72, v29
.Lsw_q_go:
	s_lshl_b32 s73, s54, 2
	s_add_i32 s74, s73, s28
	s_movk_i32 s12, 0x80
	s_ashr_i32 s13, s12, 31
	s_add_u32 s12, s0, s12
	s_addc_u32 s13, s1, s13
	s_load_dwordx2 s[12:13], s[12:13], 0x0
	v_readlane_b32 s72, v234, 44
	s_add_i32 s72, s74, s72
	s_ashr_i32 s73, s72, 31
	s_lshl_b64 s[72:73], s[72:73], 2
	s_waitcnt lgkmcnt(0)
	s_add_u32 s12, s12, s72
	s_addc_u32 s13, s13, s73
	v_mov_b64_e32 v[0:1], s[2:3]
	s_lshl_b32 s74, s74, 6
	v_mad_i64_i32 v[0:1], s[72:73], v24, s33, v[0:1]
	s_ashr_i32 s75, s74, 31
	v_lshl_add_u64 v[0:1], s[74:75], 2, v[0:1]
	v_mov_b32_e32 v23, v3
	v_lshl_add_u64 v[0:1], v[0:1], 0, v[22:23]
	s_movk_i32 s72, 0x4000
	v_add_co_u32_e32 v4, vcc, s72, v0
	s_mov_b64 s[72:73], 0x4000
	s_nop 0
	v_addc_co_u32_e32 v5, vcc, 0, v1, vcc
	global_load_dwordx4 v[4:7], v[4:5], off
	v_lshl_add_u64 v[0:1], v[0:1], 0, s[72:73]
	global_load_dwordx4 v[8:11], v[0:1], off offset:16
	global_load_dwordx4 v[12:15], v[0:1], off offset:128
	global_load_dwordx4 v[36:39], v[0:1], off offset:144
	global_load_dword v23, v3, s[12:13]
	s_and_saveexec_b64 s[26:27], s[6:7]
	s_cbranch_execz .LBB0_1148
	s_ashr_i32 s15, s14, 31
	s_lshl_b32 s55, s14, 3
	s_lshl_b32 s61, s54, 6
	s_lshl_b64 s[30:31], s[14:15], 15
	s_addk_i32 s55, 0x1f80
	s_or_b32 s30, s30, s61
	s_add_i32 s15, s39, 0xffffff81
	s_lshl_b32 s66, s14, 12
	v_and_b32_e32 v204, 60, v21
	v_ashrrev_i32_e32 v200, 4, v26
	s_and_b64 vcc, exec, s[24:25]
	s_cbranch_vccz .Lsw_prompt
	v_add_u32_e32 v0, 0, v200
	v_mov_b32_e32 v163, 0
	v_mov_b32_e32 v162, 0
	v_mov_b32_e32 v161, 0
	v_mov_b32_e32 v160, 0
	v_mov_b32_e32 v167, 0
	v_mov_b32_e32 v166, 0
	v_mov_b32_e32 v165, 0
	v_mov_b32_e32 v164, 0
	v_cmp_lt_i32_e32 vcc, s44, v0
	s_and_saveexec_b64 s[12:13], vcc
	s_xor_b64 s[12:13], exec, s[12:13]
	s_cbranch_execz .Lsw_s0_c
	s_movk_i32 s46, 0x88
	v_cmp_gt_u32_e32 vcc, s46, v0
	s_and_saveexec_b64 s[46:47], vcc
	s_cbranch_execz .Lsw_s0_b
	v_add_u32_e32 v1, s55, v0
	v_mov_b64_e32 v[160:161], s[2:3]
	v_mad_i64_i32 v[160:161], s[70:71], v1, s33, v[160:161]
	s_lshl_b32 s52, s61, 2
	v_lshl_add_u64 v[160:161], v[160:161], 0, s[52:53]
	v_lshlrev_b32_e32 v2, 2, v204
	v_lshl_add_u64 v[160:161], v[160:161], 0, v[2:3]
	v_lshl_add_u64 v[164:165], v[160:161], 0, s[58:59]
	v_add_co_u32_e32 v160, vcc, 0x5000, v160
	s_nop 1
	v_addc_co_u32_e32 v161, vcc, 0, v161, vcc
	global_load_dwordx4 v[160:163], v[160:161], off
	s_nop 0
	global_load_dwordx4 v[164:167], v[164:165], off offset:1024

; __device__ __forceinline__ void swa_phase(const Params& p, LAS unsigned char* lds8, const int e) {
;     ...
;         for (int idx = tid; idx < KROWS * 16; idx += 512) {
;             const int r = idx >> 4, c = (idx & 15) * 4;
;             f32x4 kv = (f32x4){0.f, 0.f, 0.f, 0.f}, vv = kv;
;             if (!samp) { const int pos = q0 - 127 + r; if (pos >= 0 && r < 159) { const float* src = PROJ + (size_t)(b * SEQ + pos) * IN_EVEN + 5120 + kh * 64 + c; kv = *(const f32x4*)src; vv = *(const f32x4*)(src + 256); } }
;             else if (r < 128) { const size_t o_ = ((size_t)b * 128 + r) * 256 + kh * 64 + c; kv = *(const f32x4*)(cK + o_); vv = *(const f32x4*)(cV + o_); }
;             else if (r < 136) { const float* src = PROJ + (size_t)(MP + b * DSEQ + r - 128) * IN_EVEN + 5120 + kh * 64 + c; kv = *(const f32x4*)src; vv = *(const f32x4*)(src + 256); }
.Lsw_s0_c:
	s_andn2_saveexec_b64 s[12:13], s[12:13]
	s_cbranch_execz .Lsw_s0_d
	v_ashrrev_i32_e32 v1, 31, v0
	v_lshlrev_b64 v[160:161], 8, v[0:1]
	v_lshl_add_u64 v[160:161], s[30:31], 0, v[160:161]
	v_or_b32_e32 v160, v160, v204
	v_lshlrev_b64 v[164:165], 2, v[160:161]
	v_lshl_add_u64 v[160:161], s[16:17], 0, v[164:165]
	v_lshl_add_u64 v[164:165], s[18:19], 0, v[164:165]
	global_load_dwordx4 v[160:163], v[160:161], off
	s_nop 0
	global_load_dwordx4 v[164:167], v[164:165], off
.Lsw_s0_d:
	s_or_b64 exec, exec, s[12:13]
	v_add_u32_e32 v0, 32, v200
	v_mov_b32_e32 v171, 0
	v_mov_b32_e32 v170, 0
	v_mov_b32_e32 v169, 0
	v_mov_b32_e32 v168, 0
	v_mov_b32_e32 v175, 0
	v_mov_b32_e32 v174, 0
	v_mov_b32_e32 v173, 0
	v_mov_b32_e32 v172, 0
	v_cmp_lt_i32_e32 vcc, s44, v0
	s_and_saveexec_b64 s[12:13], vcc
	s_xor_b64 s[12:13], exec, s[12:13]
	s_cbranch_execz .Lsw_s1_c
	s_movk_i32 s46, 0x88
	v_cmp_gt_u32_e32 vcc, s46, v0
	s_and_saveexec_b64 s[46:47], vcc
	s_cbranch_execz .Lsw_s1_b
	v_add_u32_e32 v1, s55, v0
	v_mov_b64_e32 v[168:169], s[2:3]
	v_mad_i64_i32 v[168:169], s[70:71], v1, s33, v[168:169]
	s_lshl_b32 s52, s61, 2
	v_lshl_add_u64 v[168:169], v[168:169], 0, s[52:53]
	v_lshlrev_b32_e32 v2, 2, v204
	v_lshl_add_u64 v[168:169], v[168:169], 0, v[2:3]
	v_lshl_add_u64 v[172:173], v[168:169], 0, s[58:59]
	v_add_co_u32_e32 v168, vcc, 0x5000, v168
	s_nop 1
	v_addc_co_u32_e32 v169, vcc, 0, v169, vcc
	global_load_dwordx4 v[168:171], v[168:169], off
	s_nop 0
	global_load_dwordx4 v[172:175], v[172:173], off offset:1024

; __device__ __forceinline__ void swa_phase(const Params& p, LAS unsigned char* lds8, const int e) {
;     ...
;         for (int idx = tid; idx < KROWS * 16; idx += 512) {
;             const int r = idx >> 4, c = (idx & 15) * 4;
;             f32x4 kv = (f32x4){0.f, 0.f, 0.f, 0.f}, vv = kv;
;             if (!samp) { const int pos = q0 - 127 + r; if (pos >= 0 && r < 159) { const float* src = PROJ + (size_t)(b * SEQ + pos) * IN_EVEN + 5120 + kh * 64 + c; kv = *(const f32x4*)src; vv = *(const f32x4*)(src + 256); } }
;             else if (r < 128) { const size_t o_ = ((size_t)b * 128 + r) * 256 + kh * 64 + c; kv = *(const f32x4*)(cK + o_); vv = *(const f32x4*)(cV + o_); }
;             else if (r < 136) { const float* src = PROJ + (size_t)(MP + b * DSEQ + r - 128) * IN_EVEN + 5120 + kh * 64 + c; kv = *(const f32x4*)src; vv = *(const f32x4*)(src + 256); }
.Lsw_s1_c:
	s_andn2_saveexec_b64 s[12:13], s[12:13]
	s_cbranch_execz .Lsw_s1_d
	v_ashrrev_i32_e32 v1, 31, v0
	v_lshlrev_b64 v[168:169], 8, v[0:1]
	v_lshl_add_u64 v[168:169], s[30:31], 0, v[168:169]
	v_or_b32_e32 v168, v168, v204
	v_lshlrev_b64 v[172:173], 2, v[168:169]
	v_lshl_add_u64 v[168:169], s[16:17], 0, v[172:173]
	v_lshl_add_u64 v[172:173], s[18:19], 0, v[172:173]
	global_load_dwordx4 v[168:171], v[168:169], off
	s_nop 0
	global_load_dwordx4 v[172:175], v[172:173], off
.Lsw_s1_d:
	s_or_b64 exec, exec, s[12:13]
	v_add_u32_e32 v0, 64, v200
	v_mov_b32_e32 v179, 0
	v_mov_b32_e32 v178, 0
	v_mov_b32_e32 v177, 0
	v_mov_b32_e32 v176, 0
	v_mov_b32_e32 v183, 0
	v_mov_b32_e32 v182, 0
	v_mov_b32_e32 v181, 0
	v_mov_b32_e32 v180, 0
	v_cmp_lt_i32_e32 vcc, s44, v0
	s_and_saveexec_b64 s[12:13], vcc
	s_xor_b64 s[12:13], exec, s[12:13]
	s_cbranch_execz .Lsw_s2_c
	s_movk_i32 s46, 0x88
	v_cmp_gt_u32_e32 vcc, s46, v0
	s_and_saveexec_b64 s[46:47], vcc
	s_cbranch_execz .Lsw_s2_b
	v_add_u32_e32 v1, s55, v0
	v_mov_b64_e32 v[176:177], s[2:3]
	v_mad_i64_i32 v[176:177], s[70:71], v1, s33, v[176:177]
	s_lshl_b32 s52, s61, 2
	v_lshl_add_u64 v[176:177], v[176:177], 0, s[52:53]
	v_lshlrev_b32_e32 v2, 2, v204
	v_lshl_add_u64 v[176:177], v[176:177], 0, v[2:3]
	v_lshl_add_u64 v[180:181], v[176:177], 0, s[58:59]
	v_add_co_u32_e32 v176, vcc, 0x5000, v176
	s_nop 1
	v_addc_co_u32_e32 v177, vcc, 0, v177, vcc
	global_load_dwordx4 v[176:179], v[176:177], off
	s_nop 0
	global_load_dwordx4 v[180:183], v[180:181], off offset:1024

; __device__ __forceinline__ void swa_phase(const Params& p, LAS unsigned char* lds8, const int e) {
;     ...
;         for (int idx = tid; idx < KROWS * 16; idx += 512) {
;             const int r = idx >> 4, c = (idx & 15) * 4;
;             f32x4 kv = (f32x4){0.f, 0.f, 0.f, 0.f}, vv = kv;
;             if (!samp) { const int pos = q0 - 127 + r; if (pos >= 0 && r < 159) { const float* src = PROJ + (size_t)(b * SEQ + pos) * IN_EVEN + 5120 + kh * 64 + c; kv = *(const f32x4*)src; vv = *(const f32x4*)(src + 256); } }
;             else if (r < 128) { const size_t o_ = ((size_t)b * 128 + r) * 256 + kh * 64 + c; kv = *(const f32x4*)(cK + o_); vv = *(const f32x4*)(cV + o_); }
;             else if (r < 136) { const float* src = PROJ + (size_t)(MP + b * DSEQ + r - 128) * IN_EVEN + 5120 + kh * 64 + c; kv = *(const f32x4*)src; vv = *(const f32x4*)(src + 256); }
.Lsw_s2_c:
	s_andn2_saveexec_b64 s[12:13], s[12:13]
	s_cbranch_execz .Lsw_s2_d
	v_ashrrev_i32_e32 v1, 31, v0
	v_lshlrev_b64 v[176:177], 8, v[0:1]
	v_lshl_add_u64 v[176:177], s[30:31], 0, v[176:177]
	v_or_b32_e32 v176, v176, v204
	v_lshlrev_b64 v[180:181], 2, v[176:177]
	v_lshl_add_u64 v[176:177], s[16:17], 0, v[180:181]
	v_lshl_add_u64 v[180:181], s[18:19], 0, v[180:181]
	global_load_dwordx4 v[176:179], v[176:177], off
	s_nop 0
	global_load_dwordx4 v[180:183], v[180:181], off
.Lsw_s2_d:
	s_or_b64 exec, exec, s[12:13]
	v_add_u32_e32 v0, 96, v200
	v_mov_b32_e32 v187, 0
	v_mov_b32_e32 v186, 0
	v_mov_b32_e32 v185, 0
	v_mov_b32_e32 v184, 0
	v_mov_b32_e32 v191, 0
	v_mov_b32_e32 v190, 0
	v_mov_b32_e32 v189, 0
	v_mov_b32_e32 v188, 0
	v_cmp_lt_i32_e32 vcc, s44, v0
	s_and_saveexec_b64 s[12:13], vcc
	s_xor_b64 s[12:13], exec, s[12:13]
	s_cbranch_execz .Lsw_s3_c
	s_movk_i32 s46, 0x88
	v_cmp_gt_u32_e32 vcc, s46, v0
	s_and_saveexec_b64 s[46:47], vcc
	s_cbranch_execz .Lsw_s3_b
	v_add_u32_e32 v1, s55, v0
	v_mov_b64_e32 v[184:185], s[2:3]
	v_mad_i64_i32 v[184:185], s[70:71], v1, s33, v[184:185]
	s_lshl_b32 s52, s61, 2
	v_lshl_add_u64 v[184:185], v[184:185], 0, s[52:53]
	v_lshlrev_b32_e32 v2, 2, v204
	v_lshl_add_u64 v[184:185], v[184:185], 0, v[2:3]
	v_lshl_add_u64 v[188:189], v[184:185], 0, s[58:59]
	v_add_co_u32_e32 v184, vcc, 0x5000, v184
	s_nop 1
	v_addc_co_u32_e32 v185, vcc, 0, v185, vcc
	global_load_dwordx4 v[184:187], v[184:185], off
	s_nop 0
	global_load_dwordx4 v[188:191], v[188:189], off offset:1024

; __device__ __forceinline__ void swa_phase(const Params& p, LAS unsigned char* lds8, const int e) {
;     ...
;         for (int idx = tid; idx < KROWS * 16; idx += 512) {
;             const int r = idx >> 4, c = (idx & 15) * 4;
;             f32x4 kv = (f32x4){0.f, 0.f, 0.f, 0.f}, vv = kv;
;             if (!samp) { const int pos = q0 - 127 + r; if (pos >= 0 && r < 159) { const float* src = PROJ + (size_t)(b * SEQ + pos) * IN_EVEN + 5120 + kh * 64 + c; kv = *(const f32x4*)src; vv = *(const f32x4*)(src + 256); } }
;             else if (r < 128) { const size_t o_ = ((size_t)b * 128 + r) * 256 + kh * 64 + c; kv = *(const f32x4*)(cK + o_); vv = *(const f32x4*)(cV + o_); }
;             else if (r < 136) { const float* src = PROJ + (size_t)(MP + b * DSEQ + r - 128) * IN_EVEN + 5120 + kh * 64 + c; kv = *(const f32x4*)src; vv = *(const f32x4*)(src + 256); }
.Lsw_s3_c:
	s_andn2_saveexec_b64 s[12:13], s[12:13]
	s_cbranch_execz .Lsw_s3_d
	v_ashrrev_i32_e32 v1, 31, v0
	v_lshlrev_b64 v[184:185], 8, v[0:1]
	v_lshl_add_u64 v[184:185], s[30:31], 0, v[184:185]
	v_or_b32_e32 v184, v184, v204
	v_lshlrev_b64 v[188:189], 2, v[184:185]
	v_lshl_add_u64 v[184:185], s[16:17], 0, v[188:189]
	v_lshl_add_u64 v[188:189], s[18:19], 0, v[188:189]
	global_load_dwordx4 v[184:187], v[184:185], off
	s_nop 0
	global_load_dwordx4 v[188:191], v[188:189], off
.Lsw_s3_d:
	s_or_b64 exec, exec, s[12:13]
	v_add_u32_e32 v0, 128, v200
	v_mov_b32_e32 v195, 0
	v_mov_b32_e32 v194, 0
	v_mov_b32_e32 v193, 0
	v_mov_b32_e32 v192, 0
	v_mov_b32_e32 v199, 0
	v_mov_b32_e32 v198, 0
	v_mov_b32_e32 v197, 0
	v_mov_b32_e32 v196, 0
	v_cmp_lt_i32_e32 vcc, s44, v0
	s_and_saveexec_b64 s[12:13], vcc
	s_xor_b64 s[12:13], exec, s[12:13]
	s_cbranch_execz .Lsw_s4_c
	s_movk_i32 s46, 0x88
	v_cmp_gt_u32_e32 vcc, s46, v0
	s_and_saveexec_b64 s[46:47], vcc
	s_cbranch_execz .Lsw_s4_b
	v_add_u32_e32 v1, s55, v0
	v_mov_b64_e32 v[192:193], s[2:3]
	v_mad_i64_i32 v[192:193], s[70:71], v1, s33, v[192:193]
	s_lshl_b32 s52, s61, 2
	v_lshl_add_u64 v[192:193], v[192:193], 0, s[52:53]
	v_lshlrev_b32_e32 v2, 2, v204
	v_lshl_add_u64 v[192:193], v[192:193], 0, v[2:3]
	v_lshl_add_u64 v[196:197], v[192:193], 0, s[58:59]
	v_add_co_u32_e32 v192, vcc, 0x5000, v192
	s_nop 1
	v_addc_co_u32_e32 v193, vcc, 0, v193, vcc
	global_load_dwordx4 v[192:195], v[192:193], off
	s_nop 0
	global_load_dwordx4 v[196:199], v[196:197], off offset:1024

; __device__ __forceinline__ void swa_phase(const Params& p, LAS unsigned char* lds8, const int e) {
;     ...
;         for (int idx = tid; idx < KROWS * 16; idx += 512) {
;             const int r = idx >> 4, c = (idx & 15) * 4;
;             f32x4 kv = (f32x4){0.f, 0.f, 0.f, 0.f}, vv = kv;
;             if (!samp) { const int pos = q0 - 127 + r; if (pos >= 0 && r < 159) { const float* src = PROJ + (size_t)(b * SEQ + pos) * IN_EVEN + 5120 + kh * 64 + c; kv = *(const f32x4*)src; vv = *(const f32x4*)(src + 256); } }
;             else if (r < 128) { const size_t o_ = ((size_t)b * 128 + r) * 256 + kh * 64 + c; kv = *(const f32x4*)(cK + o_); vv = *(const f32x4*)(cV + o_); }
;             else if (r < 136) { const float* src = PROJ + (size_t)(MP + b * DSEQ + r - 128) * IN_EVEN + 5120 + kh * 64 + c; kv = *(const f32x4*)src; vv = *(const f32x4*)(src + 256); }
.Lsw_s4_c:
	s_andn2_saveexec_b64 s[12:13], s[12:13]
	s_cbranch_execz .Lsw_s4_d
	v_ashrrev_i32_e32 v1, 31, v0
	v_lshlrev_b64 v[192:193], 8, v[0:1]
	v_lshl_add_u64 v[192:193], s[30:31], 0, v[192:193]
	v_or_b32_e32 v192, v192, v204
	v_lshlrev_b64 v[196:197], 2, v[192:193]
	v_lshl_add_u64 v[192:193], s[16:17], 0, v[196:197]
	v_lshl_add_u64 v[196:197], s[18:19], 0, v[196:197]
	global_load_dwordx4 v[192:195], v[192:193], off
	s_nop 0
	global_load_dwordx4 v[196:199], v[196:197], off

; __device__ __forceinline__ void swa_phase(const Params& p, LAS unsigned char* lds8, const int e) {
;     ...
;         for (int idx = tid; idx < KROWS * 16; idx += 512) {
;             const int r = idx >> 4, c = (idx & 15) * 4;
;             f32x4 kv = (f32x4){0.f, 0.f, 0.f, 0.f}, vv = kv;
;             if (!samp) { const int pos = q0 - 127 + r; if (pos >= 0 && r < 159) { const float* src = PROJ + (size_t)(b * SEQ + pos) * IN_EVEN + 5120 + kh * 64 + c; kv = *(const f32x4*)src; vv = *(const f32x4*)(src + 256); } }
;             else if (r < 128) { const size_t o_ = ((size_t)b * 128 + r) * 256 + kh * 64 + c; kv = *(const f32x4*)(cK + o_); vv = *(const f32x4*)(cV + o_); }
;             else if (r < 136) { const float* src = PROJ + (size_t)(MP + b * DSEQ + r - 128) * IN_EVEN + 5120 + kh * 64 + c; kv = *(const f32x4*)src; vv = *(const f32x4*)(src + 256); }
.Lsw_prompt:
	v_add_u32_e32 v0, 0, v200
	v_add_u32_e32 v1, s15, v0
	s_movk_i32 s12, 0x9f
	v_cmp_lt_i32_e32 vcc, -1, v1
	v_cmp_gt_i32_e64 s[12:13], s12, v0
	s_and_b64 s[46:47], s[12:13], vcc
	v_mov_b32_e32 v163, 0
	v_mov_b32_e32 v162, 0
	v_mov_b32_e32 v161, 0
	v_mov_b32_e32 v160, 0
	v_mov_b32_e32 v167, 0
	v_mov_b32_e32 v166, 0
	v_mov_b32_e32 v165, 0
	v_mov_b32_e32 v164, 0
	s_and_saveexec_b64 s[12:13], s[46:47]
	s_cbranch_execz .Lsw_p0
	v_add_u32_e32 v1, s66, v1
	v_mov_b64_e32 v[160:161], s[2:3]
	v_mad_i64_i32 v[160:161], s[46:47], v1, s33, v[160:161]
	s_lshl_b32 s52, s61, 2
	v_lshl_add_u64 v[160:161], v[160:161], 0, s[52:53]
	v_lshlrev_b32_e32 v2, 2, v204
	v_lshl_add_u64 v[160:161], v[160:161], 0, v[2:3]
	v_lshl_add_u64 v[164:165], v[160:161], 0, s[58:59]
	v_add_co_u32_e32 v160, vcc, 0x5000, v160
	s_nop 1
	v_addc_co_u32_e32 v161, vcc, 0, v161, vcc
	global_load_dwordx4 v[160:163], v[160:161], off
	s_nop 0
	global_load_dwordx4 v[164:167], v[164:165], off offset:1024
.Lsw_p0:
	s_or_b64 exec, exec, s[12:13]
	v_add_u32_e32 v0, 32, v200
	v_add_u32_e32 v1, s15, v0
	s_movk_i32 s12, 0x9f
	v_cmp_lt_i32_e32 vcc, -1, v1
	v_cmp_gt_i32_e64 s[12:13], s12, v0
	s_and_b64 s[46:47], s[12:13], vcc
	v_mov_b32_e32 v171, 0
	v_mov_b32_e32 v170, 0
	v_mov_b32_e32 v169, 0
	v_mov_b32_e32 v168, 0
	v_mov_b32_e32 v175, 0
	v_mov_b32_e32 v174, 0
	v_mov_b32_e32 v173, 0
	v_mov_b32_e32 v172, 0
	s_and_saveexec_b64 s[12:13], s[46:47]
	s_cbranch_execz .Lsw_p1
	v_add_u32_e32 v1, s66, v1
	v_mov_b64_e32 v[168:169], s[2:3]
	v_mad_i64_i32 v[168:169], s[46:47], v1, s33, v[168:169]
	s_lshl_b32 s52, s61, 2
	v_lshl_add_u64 v[168:169], v[168:169], 0, s[52:53]
	v_lshlrev_b32_e32 v2, 2, v204
	v_lshl_add_u64 v[168:169], v[168:169], 0, v[2:3]
	v_lshl_add_u64 v[172:173], v[168:169], 0, s[58:59]
	v_add_co_u32_e32 v168, vcc, 0x5000, v168
	s_nop 1
	v_addc_co_u32_e32 v169, vcc, 0, v169, vcc
	global_load_dwordx4 v[168:171], v[168:169], off
	s_nop 0
	global_load_dwordx4 v[172:175], v[172:173], off offset:1024
.Lsw_p1:
	s_or_b64 exec, exec, s[12:13]
	v_add_u32_e32 v0, 64, v200
	v_add_u32_e32 v1, s15, v0
	s_movk_i32 s12, 0x9f
	v_cmp_lt_i32_e32 vcc, -1, v1
	v_cmp_gt_i32_e64 s[12:13], s12, v0
	s_and_b64 s[46:47], s[12:13], vcc
	v_mov_b32_e32 v179, 0
	v_mov_b32_e32 v178, 0
	v_mov_b32_e32 v177, 0
	v_mov_b32_e32 v176, 0
	v_mov_b32_e32 v183, 0
	v_mov_b32_e32 v182, 0
	v_mov_b32_e32 v181, 0
	v_mov_b32_e32 v180, 0
	s_and_saveexec_b64 s[12:13], s[46:47]
	s_cbranch_execz .Lsw_p2
	v_add_u32_e32 v1, s66, v1
	v_mov_b64_e32 v[176:177], s[2:3]
	v_mad_i64_i32 v[176:177], s[46:47], v1, s33, v[176:177]
	s_lshl_b32 s52, s61, 2
	v_lshl_add_u64 v[176:177], v[176:177], 0, s[52:53]
	v_lshlrev_b32_e32 v2, 2, v204
	v_lshl_add_u64 v[176:177], v[176:177], 0, v[2:3]
	v_lshl_add_u64 v[180:181], v[176:177], 0, s[58:59]
	v_add_co_u32_e32 v176, vcc, 0x5000, v176
	s_nop 1
	v_addc_co_u32_e32 v177, vcc, 0, v177, vcc
	global_load_dwordx4 v[176:179], v[176:177], off
	s_nop 0
	global_load_dwordx4 v[180:183], v[180:181], off offset:1024
.Lsw_p2:
	s_or_b64 exec, exec, s[12:13]
	v_add_u32_e32 v0, 96, v200
	v_add_u32_e32 v1, s15, v0
	s_movk_i32 s12, 0x9f
	v_cmp_lt_i32_e32 vcc, -1, v1
	v_cmp_gt_i32_e64 s[12:13], s12, v0
	s_and_b64 s[46:47], s[12:13], vcc
	v_mov_b32_e32 v187, 0
	v_mov_b32_e32 v186, 0
	v_mov_b32_e32 v185, 0
	v_mov_b32_e32 v184, 0
	v_mov_b32_e32 v191, 0
	v_mov_b32_e32 v190, 0
	v_mov_b32_e32 v189, 0
	v_mov_b32_e32 v188, 0
	s_and_saveexec_b64 s[12:13], s[46:47]
	s_cbranch_execz .Lsw_p3
	v_add_u32_e32 v1, s66, v1
	v_mov_b64_e32 v[184:185], s[2:3]
	v_mad_i64_i32 v[184:185], s[46:47], v1, s33, v[184:185]
	s_lshl_b32 s52, s61, 2
	v_lshl_add_u64 v[184:185], v[184:185], 0, s[52:53]
	v_lshlrev_b32_e32 v2, 2, v204
	v_lshl_add_u64 v[184:185], v[184:185], 0, v[2:3]
	v_lshl_add_u64 v[188:189], v[184:185], 0, s[58:59]
	v_add_co_u32_e32 v184, vcc, 0x5000, v184
	s_nop 1
	v_addc_co_u32_e32 v185, vcc, 0, v185, vcc
	global_load_dwordx4 v[184:187], v[184:185], off
	s_nop 0
	global_load_dwordx4 v[188:191], v[188:189], off offset:1024
.Lsw_p3:
	s_or_b64 exec, exec, s[12:13]
	v_add_u32_e32 v0, 128, v200
	v_add_u32_e32 v1, s15, v0
	s_movk_i32 s12, 0x9f
	v_cmp_lt_i32_e32 vcc, -1, v1
	v_cmp_gt_i32_e64 s[12:13], s12, v0
	s_and_b64 s[46:47], s[12:13], vcc
	v_mov_b32_e32 v195, 0
	v_mov_b32_e32 v194, 0
	v_mov_b32_e32 v193, 0
	v_mov_b32_e32 v192, 0
	v_mov_b32_e32 v199, 0
	v_mov_b32_e32 v198, 0
	v_mov_b32_e32 v197, 0
	v_mov_b32_e32 v196, 0
	s_and_saveexec_b64 s[12:13], s[46:47]
	s_cbranch_execz .Lsw_p4
	v_add_u32_e32 v1, s66, v1
	v_mov_b64_e32 v[192:193], s[2:3]
	v_mad_i64_i32 v[192:193], s[46:47], v1, s33, v[192:193]
	s_lshl_b32 s52, s61, 2
	v_lshl_add_u64 v[192:193], v[192:193], 0, s[52:53]
	v_lshlrev_b32_e32 v2, 2, v204
	v_lshl_add_u64 v[192:193], v[192:193], 0, v[2:3]
	v_lshl_add_u64 v[196:197], v[192:193], 0, s[58:59]
	v_add_co_u32_e32 v192, vcc, 0x5000, v192
	s_nop 1
	v_addc_co_u32_e32 v193, vcc, 0, v193, vcc
	global_load_dwordx4 v[192:195], v[192:193], off
	s_nop 0
	global_load_dwordx4 v[196:199], v[196:197], off offset:1024

; #define LAS __attribute__((address_space(3)))
; __device__ __forceinline__ unsigned pk2(float lo, float hi) { f32x2c v = {lo, hi}; return __builtin_bit_cast(unsigned, __builtin_convertvector(v, bf16x2c)); }
; __device__ __forceinline__ unsigned short bf1(float f) { return (unsigned short)(pk2(f, 0.f) & 0xffffu); }
; __device__ __forceinline__ void swa_phase(const Params& p, LAS unsigned char* lds8, const int e) {
;     ...
;             u32x2 kw; kw.x = pk2(kv[0], kv[1]); kw.y = pk2(kv[2], kv[3]); *(LAS u32x2*)(Kb + r * SW_KS + c) = kw;
;             VTb[(c + 0) * SW_VS + r] = bf1(vv[0]); VTb[(c + 1) * SW_VS + r] = bf1(vv[1]); VTb[(c + 2) * SW_VS + r] = bf1(vv[2]); VTb[(c + 3) * SW_VS + r] = bf1(vv[3]);
;         }
.Lsw_write:
	s_waitcnt vmcnt(0)
	v_add_u32_e32 v0, 0, v200
	v_mul_lo_u32 v1, v0, s51
	v_lshlrev_b32_e32 v2, 1, v204
	v_cvt_pk_bf16_f32 v160, v160, v161
	v_cvt_pk_bf16_f32 v161, v162, v163
	v_add3_u32 v1, 0, v1, v2
	v_mul_u32_u24_e32 v2, 0x150, v204
	v_lshlrev_b32_e32 v0, 1, v0
	ds_write_b64 v1, v[160:161]
	v_cvt_pk_bf16_f32 v1, v164, s0
	v_add3_u32 v0, 0, v2, v0
	ds_write_b16 v0, v1 offset:23040
	v_cvt_pk_bf16_f32 v1, v165, s0
	ds_write_b16 v0, v1 offset:23376
	v_cvt_pk_bf16_f32 v1, v166, s0
	ds_write_b16 v0, v1 offset:23712
	v_cvt_pk_bf16_f32 v1, v167, s0
	ds_write_b16 v0, v1 offset:24048
	v_add_u32_e32 v0, 32, v200
	v_mul_lo_u32 v1, v0, s51
	v_lshlrev_b32_e32 v2, 1, v204
	v_cvt_pk_bf16_f32 v168, v168, v169
	v_cvt_pk_bf16_f32 v169, v170, v171
	v_add3_u32 v1, 0, v1, v2
	v_mul_u32_u24_e32 v2, 0x150, v204
	v_lshlrev_b32_e32 v0, 1, v0
	ds_write_b64 v1, v[168:169]
	v_cvt_pk_bf16_f32 v1, v172, s0
	v_add3_u32 v0, 0, v2, v0
	ds_write_b16 v0, v1 offset:23040
	v_cvt_pk_bf16_f32 v1, v173, s0
	ds_write_b16 v0, v1 offset:23376
	v_cvt_pk_bf16_f32 v1, v174, s0
	ds_write_b16 v0, v1 offset:23712
	v_cvt_pk_bf16_f32 v1, v175, s0
	ds_write_b16 v0, v1 offset:24048
	v_add_u32_e32 v0, 64, v200
	v_mul_lo_u32 v1, v0, s51
	v_lshlrev_b32_e32 v2, 1, v204
	v_cvt_pk_bf16_f32 v176, v176, v177
	v_cvt_pk_bf16_f32 v177, v178, v179
	v_add3_u32 v1, 0, v1, v2
	v_mul_u32_u24_e32 v2, 0x150, v204
	v_lshlrev_b32_e32 v0, 1, v0
	ds_write_b64 v1, v[176:177]
	v_cvt_pk_bf16_f32 v1, v180, s0
	v_add3_u32 v0, 0, v2, v0
	ds_write_b16 v0, v1 offset:23040
	v_cvt_pk_bf16_f32 v1, v181, s0
	ds_write_b16 v0, v1 offset:23376
	v_cvt_pk_bf16_f32 v1, v182, s0
	ds_write_b16 v0, v1 offset:23712
	v_cvt_pk_bf16_f32 v1, v183, s0
	ds_write_b16 v0, v1 offset:24048
	v_add_u32_e32 v0, 96, v200
	v_mul_lo_u32 v1, v0, s51
	v_lshlrev_b32_e32 v2, 1, v204
	v_cvt_pk_bf16_f32 v184, v184, v185
	v_cvt_pk_bf16_f32 v185, v186, v187
	v_add3_u32 v1, 0, v1, v2
	v_mul_u32_u24_e32 v2, 0x150, v204
	v_lshlrev_b32_e32 v0, 1, v0
	ds_write_b64 v1, v[184:185]
	v_cvt_pk_bf16_f32 v1, v188, s0
	v_add3_u32 v0, 0, v2, v0
	ds_write_b16 v0, v1 offset:23040
	v_cvt_pk_bf16_f32 v1, v189, s0
	ds_write_b16 v0, v1 offset:23376
	v_cvt_pk_bf16_f32 v1, v190, s0
	ds_write_b16 v0, v1 offset:23712
	v_cvt_pk_bf16_f32 v1, v191, s0
	ds_write_b16 v0, v1 offset:24048
	v_add_u32_e32 v0, 128, v200
	v_mul_lo_u32 v1, v0, s51
	v_lshlrev_b32_e32 v2, 1, v204
	v_cvt_pk_bf16_f32 v192, v192, v193
	v_cvt_pk_bf16_f32 v193, v194, v195
	v_add3_u32 v1, 0, v1, v2
	v_mul_u32_u24_e32 v2, 0x150, v204
	v_lshlrev_b32_e32 v0, 1, v0
	ds_write_b64 v1, v[192:193]
	v_cvt_pk_bf16_f32 v1, v196, s0
	v_add3_u32 v0, 0, v2, v0
	ds_write_b16 v0, v1 offset:23040
	v_cvt_pk_bf16_f32 v1, v197, s0
	ds_write_b16 v0, v1 offset:23376
	v_cvt_pk_bf16_f32 v1, v198, s0
	ds_write_b16 v0, v1 offset:23712
	v_cvt_pk_bf16_f32 v1, v199, s0
	ds_write_b16 v0, v1 offset:24048

; #define LAS __attribute__((address_space(3)))
; __device__ __forceinline__ unsigned pk2(float lo, float hi) { f32x2c v = {lo, hi}; return __builtin_bit_cast(unsigned, __builtin_convertvector(v, bf16x2c)); }
; __device__ __forceinline__ void swa_phase(const Params& p, LAS unsigned char* lds8, const int e) {
;     ...
;             const int head = kh * 4 + hh;
;             const float sink = IN(16)[e * 16 + head];
;             bf16x8 qf[2];
;             { const float* qp = PROJ + (size_t)mtok * IN_EVEN + 4096 + head * 64 + 8 * fq;
; #pragma unroll
;               for (int ks = 0; ks < 2; ++ks) { const f32x4 a = *(const f32x4*)(qp + 32 * ks) * 0.125f, c2 = *(const f32x4*)(qp + 32 * ks + 4) * 0.125f;
;                   u32x4 w; w.x = pk2(a[0], a[1]); w.y = pk2(a[2], a[3]); w.z = pk2(c2[0], c2[1]); w.w = pk2(c2[2], c2[3]); qf[ks] = __builtin_bit_cast(bf16x8, w); } }
;             const int kt0 = samp ? 0 : sub;
;             f32x4 S[10]; float mloc = -1e30f;
; #pragma unroll
;             for (int t = 0; t < 10; ++t) {
;                 S[t] = (f32x4){0.f, 0.f, 0.f, 0.f};
;                 if (t < 9) {
; #pragma unroll
;                     for (int ks = 0; ks < 2; ++ks) { const bf16x8 a = *(const LAS bf16x8*)(Kb + (16 * (kt0 + t) + fr) * SW_KS + 32 * ks + 8 * fq);
;                         S[t] = __builtin_amdgcn_mfma_f32_16x16x32_bf16(a, qf[ks], S[t], 0, 0, 0); }
.LBB0_1153:
	s_add_i32 s24, s15, s28
	s_lshl_b32 s24, s24, 6
	s_ashr_i32 s25, s24, 31
	s_lshl_b32 s31, s30, 4
	v_or_b32_e32 v1, s31, v27
	v_mad_u32_u24 v1, v1, s51, v33
	ds_read_b128 v[40:43], v1
	ds_read_b128 v[44:47], v1 offset:64
	s_mov_b32 s12, 0x3e000000
	v_cndmask_b32_e64 v0, v30, v31, s[10:11]
	s_sub_i32 s39, 0x7e, s39
	v_or_b32_e32 v18, s31, v20
	v_sub_u32_e32 v16, v0, v18
	v_cmp_lt_i32_e32 vcc, s39, v18
	s_waitcnt vmcnt(3)
	v_pk_mul_f32 v[10:11], v[10:11], s[12:13] op_sel_hi:[1,0]
	v_pk_mul_f32 v[6:7], v[6:7], s[12:13] op_sel_hi:[1,0]
	v_pk_mul_f32 v[4:5], v[4:5], s[12:13] op_sel_hi:[1,0]
	v_pk_mul_f32 v[8:9], v[8:9], s[12:13] op_sel_hi:[1,0]
	s_waitcnt vmcnt(2)
	v_pk_mul_f32 v[12:13], v[12:13], s[12:13] op_sel_hi:[1,0]
	v_cvt_pk_bf16_f32 v4, v4, v5
	v_cvt_pk_bf16_f32 v5, v6, v7
	v_cvt_pk_bf16_f32 v6, v8, v9
	v_cvt_pk_bf16_f32 v7, v10, v11
	v_pk_mul_f32 v[48:49], v[14:15], s[12:13] op_sel_hi:[1,0]
	v_cvt_pk_bf16_f32 v8, v12, v13
	s_waitcnt lgkmcnt(1)
	v_mfma_f32_16x16x32_bf16 v[12:15], v[40:43], v[4:7], 0
	s_waitcnt vmcnt(1)
	v_pk_mul_f32 v[38:39], v[38:39], s[12:13] op_sel_hi:[1,0]
	v_pk_mul_f32 v[36:37], v[36:37], s[12:13] op_sel_hi:[1,0]
	v_cndmask_b32_e64 v2, 0, 1, vcc
	v_cmp_gt_u32_e32 vcc, s68, v16
	v_cvt_pk_bf16_f32 v9, v48, v49
	v_cvt_pk_bf16_f32 v10, v36, v37
	v_cvt_pk_bf16_f32 v11, v38, v39
	v_cndmask_b32_e64 v1, 0, 1, vcc
	s_and_b64 vcc, s[10:11], vcc
	s_waitcnt lgkmcnt(0)
	v_mfma_f32_16x16x32_bf16 v[12:15], v[44:47], v[8:11], v[12:15]
	v_cndmask_b32_e32 v1, v1, v2, vcc
	v_and_b32_e32 v1, 1, v1
	v_cmp_eq_u32_e32 vcc, 1, v1
	v_mov_b32_e32 v1, 0xf149f2ca
	v_mov_b32_e32 v2, 0xf149f2ca
	s_and_saveexec_b64 s[12:13], vcc
	s_cbranch_execz .LBB0_1155
	v_lshlrev_b32_e32 v2, 4, v16
	v_and_b32_e32 v2, 0x7f0, v2
	v_add_u32_e32 v2, s35, v2
	ds_read_b32 v2, v2 offset:44544
	s_waitcnt lgkmcnt(0)
	v_add_f32_e32 v2, v12, v2
